# work rebalancing: 3 k-blocks of w_in on the FFN1-gu dedicated converters, 200 gate2 items shifted to the in-proj converters
# baseline (speedup 1.0000x reference)
.LBB0_29:
	v_mov_b32_e32 v16, v183
	s_cmpk_gt_i32 s4, 0x3064
	v_readfirstlane_b32 s3, v16
	s_cbranch_scc1 .LBB0_427
	s_cmpk_lt_i32 s4, 0xb00
	s_mov_b32 s5, 1
	s_cbranch_scc1 .LBB0_34
	s_cmpk_gt_u32 s4, 0x15ff
	s_cbranch_scc0 .LBB0_35
	v_readlane_b32 s16, v234, 40
	v_readlane_b32 s22, v234, 46
	v_readlane_b32 s23, v234, 47
	v_readlane_b32 s24, v234, 48
	v_readlane_b32 s25, v234, 49
	s_add_i32 s12, s4, 0xffffea00
	v_readlane_b32 s17, v234, 41
	v_readlane_b32 s18, v234, 42
	v_readlane_b32 s19, v234, 43
	v_readlane_b32 s20, v234, 44
	v_readlane_b32 s21, v234, 45
	v_readlane_b32 s26, v234, 50
	v_readlane_b32 s27, v234, 51
	v_readlane_b32 s28, v234, 52
	v_readlane_b32 s29, v234, 53
	v_readlane_b32 s30, v234, 54
	v_readlane_b32 s31, v234, 55
	s_mov_b64 s[8:9], s[22:23]
	s_mov_b64 s[10:11], s[24:25]
	s_cbranch_execz .LBB0_36
	s_mov_b64 s[6:7], 0x4400000
	s_movk_i32 s28, 0x3a28
	s_mov_b32 s5, 3
	s_branch .LBB0_37

.LBB0_79:
	s_add_i32 s41, s4, s50
	s_cmpk_lt_i32 s41, 0x3065
	s_cselect_b64 s[10:11], -1, 0
	s_cmpk_gt_i32 s41, 0x3064
	s_cselect_b64 s[8:9], -1, 0
	s_and_b64 vcc, exec, s[8:9]
	s_mov_b64 s[12:13], s[6:7]
	s_mov_b32 s42, s28
	s_mov_b32 s43, s5
	s_mov_b32 s44, s2
	s_mov_b32 s45, s29
	s_cbranch_vccnz .LBB0_121
	s_cmpk_lt_i32 s41, 0xb00
	s_cbranch_scc1 .LBB0_84
	s_cmpk_gt_u32 s41, 0x15ff
	s_cbranch_scc0 .LBB0_85
	v_readlane_b32 s12, v234, 40
	v_readlane_b32 s14, v234, 42
	v_readlane_b32 s15, v234, 43
	v_readlane_b32 s16, v234, 44
	v_readlane_b32 s17, v234, 45
	v_readlane_b32 s18, v234, 46
	v_readlane_b32 s19, v234, 47
	v_readlane_b32 s20, v234, 48
	v_readlane_b32 s21, v234, 49
	s_add_i32 s3, s41, 0xffffea00
	v_readlane_b32 s13, v234, 41
	v_readlane_b32 s22, v234, 50
	v_readlane_b32 s23, v234, 51
	v_readlane_b32 s24, v234, 52
	v_readlane_b32 s25, v234, 53
	v_readlane_b32 s26, v234, 54
	v_readlane_b32 s27, v234, 55
	s_mov_b64 s[14:15], s[18:19]
	s_mov_b64 s[16:17], s[20:21]
	s_cbranch_execz .LBB0_86
	s_mov_b64 s[12:13], 0x4400000
	s_movk_i32 s42, 0x3a28
	s_mov_b32 s43, 3
	s_branch .LBB0_87

.LBB0_511:
	v_readlane_b32 s0, v234, 12
	v_writelane_b32 v233, s52, 12
	s_abs_i32 s52, s0
	v_cvt_f32_u32_e32 v0, s52
	s_sub_i32 s0, 0, s52
	v_readlane_b32 s1, v234, 13
	v_writelane_b32 v233, s50, 13
	v_rcp_iflag_f32_e32 v0, v0
	s_nop 0
	v_writelane_b32 v233, s51, 14
	v_mul_f32_e32 v0, 0x4f7ffffe, v0
	v_cvt_u32_f32_e32 v0, v0
	s_nop 0
	v_readfirstlane_b32 s53, v0
	s_mul_i32 s0, s0, s53
	s_mul_hi_u32 s0, s53, s0
	s_add_i32 s53, s53, s0
	s_mul_hi_u32 s0, s53, 0x5ac
	s_mul_i32 s0, s0, s52
	s_sub_i32 s0, 0x5ac, s0
	s_sub_i32 s1, s0, s52
	s_cmp_ge_u32 s0, s52
	s_cselect_b32 s0, s1, s0
	s_sub_i32 s1, s0, s52
	s_cmp_ge_u32 s0, s52
	s_movk_i32 s5, 0xf2
	s_cmp_eq_u32 s5, 0
	s_cselect_b64 s[0:1], -1, 0
	s_cmp_lt_i32 s4, s5
	s_cselect_b64 s[2:3], -1, 0
	s_or_b64 s[0:1], s[0:1], s[2:3]
	s_and_b64 vcc, exec, s[0:1]
	s_cbranch_vccnz .LBB0_931
	v_readlane_b32 s2, v234, 14
	v_readlane_b32 s3, v234, 12
	v_readfirstlane_b32 s0, v183
	s_sub_i32 s2, s2, s5
	s_sub_i32 s3, s3, s5
	s_lshl_b32 s2, s2, 3
	s_lshr_b32 s0, s0, 6
	s_add_i32 s4, s2, s0
	s_lshl_b32 s33, s3, 3
	s_cmp_ge_u32 s4, 0x12cf
	s_cbranch_scc1 .LBB0_931
	v_readlane_b32 s30, v234, 2
	v_readlane_b32 s31, v234, 3
	v_and_b32_e32 v176, 7, v183
	v_bfe_u32 v185, v183, 3, 3
	v_lshlrev_b32_e32 v177, 4, v185
	v_lshlrev_b32_e32 v186, 4, v176
	s_cmp_lt_u32 s4, 0x12cf
	s_cbranch_scc1 .Lcv1_p0_go
	s_mov_b32 s22, 0
	s_branch .Lcv1_p0_end

.Lcv1_p0_seg1:
	s_cmp_lt_u32 s4, 0xdbb
	s_cbranch_scc0 .Lcv1_p0_seg2
	s_add_u32 s34, s4, 0xf65
	s_mul_i32 s39, s34, 18002
	s_lshr_b32 s39, s39, 22
	s_mul_i32 s40, s39, 233
	s_sub_u32 s40, s34, s40
	v_readlane_b32 s0, v234, 48
	v_readlane_b32 s1, v234, 49
	s_mul_i32 s2, s39, 0x3a2800
	s_lshl_b32 s3, s40, 8
	s_add_u32 s2, s2, s3
	s_add_u32 s0, s0, s2
	s_addc_u32 s1, s1, 0
	s_mov_b32 s41, 0xe8a0
	s_mov_b32 s42, 0x74500
	s_lshl_b32 s2, s40, 18
	s_lshl_b32 s3, s39, 7
	s_add_u32 s2, s2, s3
	s_add_u32 s2, s2, 0x43d8000
	s_add_u32 s16, s30, s2
	s_addc_u32 s17, s31, 0
	s_mov_b32 s20, 0x1000
	s_mov_b32 s21, 0x4000
	s_lshl_b32 s23, s40, 6
	s_mov_b64 s[46:47], -1
	s_cmp_eq_u32 s40, 232
	s_cbranch_scc0 .Lcv1_p0_full1
	s_mov_b64 s[46:47], 0xffff

.Lcv1_p0_seg2:
	s_sub_u32 s34, s4, 0xdbb
	s_mul_i32 s39, s34, 5958
	s_lshr_b32 s39, s39, 19
	s_mul_i32 s40, s39, 88
	s_sub_u32 s40, s34, s40
	v_readlane_b32 s0, v234, 4
	v_readlane_b32 s1, v234, 5
	s_mul_i32 s2, s39, 0x160000
	s_lshl_b32 s3, s40, 8
	s_add_u32 s2, s2, s3
	s_add_u32 s0, s0, s2
	s_addc_u32 s1, s1, 0
	s_mov_b32 s41, 0x5800
	s_mov_b32 s42, 0x2c000
	s_lshr_b32 s2, s40, 1
	s_lshl_b32 s2, s2, 8
	s_and_b32 s3, s40, 1
	s_lshl_b32 s3, s3, 6
	s_add_u32 s2, s2, s3
	s_mul_i32 s2, s2, 0x1000
	s_lshl_b32 s3, s39, 7
	s_add_u32 s2, s2, s3
	s_add_u32 s2, s2, 0x8700000
	s_add_u32 s16, s30, s2
	s_addc_u32 s17, s31, 0
	s_mov_b32 s20, 0x1000
	s_mov_b32 s21, 0x4000
	s_mov_b32 s23, -1
	v_readlane_b32 s8, v233, 6
	v_readlane_b32 s9, v233, 7
	s_lshl_b32 s3, s39, 8
	s_mov_b32 s22, 18
	s_nop 0
	s_add_u32 s8, s8, s3
	s_addc_u32 s9, s9, 0

.Lcv1_p0_end:
	s_cmp_lt_u32 s4, 0x12cf
	s_cbranch_scc1 .Lcv1_p1_go
	s_mov_b32 s28, 0
	s_branch .Lcv1_p1_end

.Lcv1_p1_seg1:
	s_cmp_lt_u32 s4, 0xdbb
	s_cbranch_scc0 .Lcv1_p1_seg2
	s_add_u32 s34, s4, 0xf65
	s_mul_i32 s39, s34, 18002
	s_lshr_b32 s39, s39, 22
	s_mul_i32 s40, s39, 233
	s_sub_u32 s40, s34, s40
	v_readlane_b32 s0, v234, 48
	v_readlane_b32 s1, v234, 49
	s_mul_i32 s2, s39, 0x3a2800
	s_lshl_b32 s3, s40, 8
	s_add_u32 s2, s2, s3
	s_add_u32 s0, s0, s2
	s_addc_u32 s1, s1, 0
	s_mov_b32 s41, 0xe8a0
	s_mov_b32 s42, 0x74500
	s_lshl_b32 s2, s40, 18
	s_lshl_b32 s3, s39, 7
	s_add_u32 s2, s2, s3
	s_add_u32 s2, s2, 0x43d8000
	s_add_u32 s24, s30, s2
	s_addc_u32 s25, s31, 0
	s_mov_b32 s26, 0x1000
	s_mov_b32 s27, 0x4000
	s_lshl_b32 s29, s40, 6
	s_mov_b64 s[46:47], -1
	s_cmp_eq_u32 s40, 232
	s_cbranch_scc0 .Lcv1_p1_full1
	s_mov_b64 s[46:47], 0xffff

.Lcv1_p1_seg2:
	s_sub_u32 s34, s4, 0xdbb
	s_mul_i32 s39, s34, 5958
	s_lshr_b32 s39, s39, 19
	s_mul_i32 s40, s39, 88
	s_sub_u32 s40, s34, s40
	v_readlane_b32 s0, v234, 4
	v_readlane_b32 s1, v234, 5
	s_mul_i32 s2, s39, 0x160000
	s_lshl_b32 s3, s40, 8
	s_add_u32 s2, s2, s3
	s_add_u32 s0, s0, s2
	s_addc_u32 s1, s1, 0
	s_mov_b32 s41, 0x5800
	s_mov_b32 s42, 0x2c000
	s_lshr_b32 s2, s40, 1
	s_lshl_b32 s2, s2, 8
	s_and_b32 s3, s40, 1
	s_lshl_b32 s3, s3, 6
	s_add_u32 s2, s2, s3
	s_mul_i32 s2, s2, 0x1000
	s_lshl_b32 s3, s39, 7
	s_add_u32 s2, s2, s3
	s_add_u32 s2, s2, 0x8700000
	s_add_u32 s24, s30, s2
	s_addc_u32 s25, s31, 0
	s_mov_b32 s26, 0x1000
	s_mov_b32 s27, 0x4000
	s_mov_b32 s29, -1
	v_readlane_b32 s8, v233, 6
	v_readlane_b32 s9, v233, 7
	s_lshl_b32 s3, s39, 8
	s_mov_b32 s28, 18
	s_nop 0
	s_add_u32 s8, s8, s3
	s_addc_u32 s9, s9, 0

.Lcv1_pa_plain:
	v_pk_mul_f32 v[0:1], v[0:1], v[128:129] op_sel_hi:[1,0]
	v_pk_mul_f32 v[2:3], v[2:3], v[128:129] op_sel_hi:[1,0]
	v_pk_mul_f32 v[4:5], v[4:5], v[128:129] op_sel_hi:[1,0]
	v_pk_mul_f32 v[6:7], v[6:7], v[128:129] op_sel_hi:[1,0]
	v_pk_mul_f32 v[8:9], v[8:9], v[128:129] op_sel:[0,1]
	v_pk_mul_f32 v[10:11], v[10:11], v[128:129] op_sel:[0,1]
	v_pk_mul_f32 v[12:13], v[12:13], v[128:129] op_sel:[0,1]
	v_pk_mul_f32 v[14:15], v[14:15], v[128:129] op_sel:[0,1]
	v_pk_mul_f32 v[16:17], v[16:17], v[130:131] op_sel_hi:[1,0]
	v_pk_mul_f32 v[18:19], v[18:19], v[130:131] op_sel_hi:[1,0]
	v_pk_mul_f32 v[20:21], v[20:21], v[130:131] op_sel_hi:[1,0]
	v_pk_mul_f32 v[22:23], v[22:23], v[130:131] op_sel_hi:[1,0]
	v_pk_mul_f32 v[24:25], v[24:25], v[130:131] op_sel:[0,1]
	v_pk_mul_f32 v[26:27], v[26:27], v[130:131] op_sel:[0,1]
	v_pk_mul_f32 v[28:29], v[28:29], v[130:131] op_sel:[0,1]
	v_pk_mul_f32 v[30:31], v[30:31], v[130:131] op_sel:[0,1]
	v_pk_mul_f32 v[32:33], v[32:33], v[132:133] op_sel_hi:[1,0]
	v_pk_mul_f32 v[34:35], v[34:35], v[132:133] op_sel_hi:[1,0]
	v_pk_mul_f32 v[36:37], v[36:37], v[132:133] op_sel_hi:[1,0]
	v_pk_mul_f32 v[38:39], v[38:39], v[132:133] op_sel_hi:[1,0]
	v_pk_mul_f32 v[40:41], v[40:41], v[132:133] op_sel:[0,1]
	v_pk_mul_f32 v[42:43], v[42:43], v[132:133] op_sel:[0,1]
	v_pk_mul_f32 v[44:45], v[44:45], v[132:133] op_sel:[0,1]
	v_pk_mul_f32 v[46:47], v[46:47], v[132:133] op_sel:[0,1]
	v_pk_mul_f32 v[48:49], v[48:49], v[134:135] op_sel_hi:[1,0]
	v_pk_mul_f32 v[50:51], v[50:51], v[134:135] op_sel_hi:[1,0]
	v_pk_mul_f32 v[52:53], v[52:53], v[134:135] op_sel_hi:[1,0]
	v_pk_mul_f32 v[54:55], v[54:55], v[134:135] op_sel_hi:[1,0]
	v_pk_mul_f32 v[56:57], v[56:57], v[134:135] op_sel:[0,1]
	v_pk_mul_f32 v[58:59], v[58:59], v[134:135] op_sel:[0,1]
	v_pk_mul_f32 v[60:61], v[60:61], v[134:135] op_sel:[0,1]
	v_pk_mul_f32 v[62:63], v[62:63], v[134:135] op_sel:[0,1]
	v_cvt_pk_bf16_f32 v144, v0, v8
	v_cvt_pk_bf16_f32 v145, v16, v24
	v_cvt_pk_bf16_f32 v146, v32, v40
	v_cvt_pk_bf16_f32 v147, v48, v56
	global_store_dwordx4 v179, v[144:147], s[16:17]
	v_cvt_pk_bf16_f32 v148, v1, v9
	v_cvt_pk_bf16_f32 v149, v17, v25
	v_cvt_pk_bf16_f32 v150, v33, v41
	v_cvt_pk_bf16_f32 v151, v49, v57
	s_add_u32 s16, s16, s20
	s_addc_u32 s17, s17, 0
	global_store_dwordx4 v179, v[148:151], s[16:17]
	v_cvt_pk_bf16_f32 v152, v2, v10
	v_cvt_pk_bf16_f32 v153, v18, v26
	v_cvt_pk_bf16_f32 v154, v34, v42
	v_cvt_pk_bf16_f32 v155, v50, v58
	s_add_u32 s16, s16, s20
	s_addc_u32 s17, s17, 0
	global_store_dwordx4 v179, v[152:155], s[16:17]
	v_cvt_pk_bf16_f32 v156, v3, v11
	v_cvt_pk_bf16_f32 v157, v19, v27
	v_cvt_pk_bf16_f32 v158, v35, v43
	v_cvt_pk_bf16_f32 v159, v51, v59
	s_add_u32 s16, s16, s20
	s_addc_u32 s17, s17, 0
	global_store_dwordx4 v179, v[156:159], s[16:17]
	s_mov_b64 exec, s[48:49]
	v_cvt_pk_bf16_f32 v160, v4, v12
	v_cvt_pk_bf16_f32 v161, v20, v28
	v_cvt_pk_bf16_f32 v162, v36, v44
	v_cvt_pk_bf16_f32 v163, v52, v60
	s_mul_i32 s2, s20, 29
	s_add_u32 s16, s16, s2
	s_addc_u32 s17, s17, 0
	global_store_dwordx4 v184, v[160:163], s[16:17]
	v_cvt_pk_bf16_f32 v164, v5, v13
	v_cvt_pk_bf16_f32 v165, v21, v29
	v_cvt_pk_bf16_f32 v166, v37, v45
	v_cvt_pk_bf16_f32 v167, v53, v61
	s_add_u32 s16, s16, s20
	s_addc_u32 s17, s17, 0
	global_store_dwordx4 v184, v[164:167], s[16:17]
	v_cvt_pk_bf16_f32 v168, v6, v14
	v_cvt_pk_bf16_f32 v169, v22, v30
	v_cvt_pk_bf16_f32 v170, v38, v46
	v_cvt_pk_bf16_f32 v171, v54, v62
	s_add_u32 s16, s16, s20
	s_addc_u32 s17, s17, 0
	global_store_dwordx4 v184, v[168:171], s[16:17]
	v_cvt_pk_bf16_f32 v172, v7, v15
	v_cvt_pk_bf16_f32 v173, v23, v31
	v_cvt_pk_bf16_f32 v174, v39, v47
	v_cvt_pk_bf16_f32 v175, v55, v63
	s_add_u32 s16, s16, s20
	s_addc_u32 s17, s17, 0
	global_store_dwordx4 v184, v[172:175], s[16:17]
	s_mov_b64 exec, -1
	s_cmp_lt_u32 s4, 0x12cf
	s_cbranch_scc1 .Lcv1_la_go
	s_mov_b32 s22, 0
	s_branch .Lcv1_la_end

.Lcv1_pb_plain:
	v_pk_mul_f32 v[64:65], v[64:65], v[136:137] op_sel_hi:[1,0]
	v_pk_mul_f32 v[66:67], v[66:67], v[136:137] op_sel_hi:[1,0]
	v_pk_mul_f32 v[68:69], v[68:69], v[136:137] op_sel_hi:[1,0]
	v_pk_mul_f32 v[70:71], v[70:71], v[136:137] op_sel_hi:[1,0]
	v_pk_mul_f32 v[72:73], v[72:73], v[136:137] op_sel:[0,1]
	v_pk_mul_f32 v[74:75], v[74:75], v[136:137] op_sel:[0,1]
	v_pk_mul_f32 v[76:77], v[76:77], v[136:137] op_sel:[0,1]
	v_pk_mul_f32 v[78:79], v[78:79], v[136:137] op_sel:[0,1]
	v_pk_mul_f32 v[80:81], v[80:81], v[138:139] op_sel_hi:[1,0]
	v_pk_mul_f32 v[82:83], v[82:83], v[138:139] op_sel_hi:[1,0]
	v_pk_mul_f32 v[84:85], v[84:85], v[138:139] op_sel_hi:[1,0]
	v_pk_mul_f32 v[86:87], v[86:87], v[138:139] op_sel_hi:[1,0]
	v_pk_mul_f32 v[88:89], v[88:89], v[138:139] op_sel:[0,1]
	v_pk_mul_f32 v[90:91], v[90:91], v[138:139] op_sel:[0,1]
	v_pk_mul_f32 v[92:93], v[92:93], v[138:139] op_sel:[0,1]
	v_pk_mul_f32 v[94:95], v[94:95], v[138:139] op_sel:[0,1]
	v_pk_mul_f32 v[96:97], v[96:97], v[140:141] op_sel_hi:[1,0]
	v_pk_mul_f32 v[98:99], v[98:99], v[140:141] op_sel_hi:[1,0]
	v_pk_mul_f32 v[100:101], v[100:101], v[140:141] op_sel_hi:[1,0]
	v_pk_mul_f32 v[102:103], v[102:103], v[140:141] op_sel_hi:[1,0]
	v_pk_mul_f32 v[104:105], v[104:105], v[140:141] op_sel:[0,1]
	v_pk_mul_f32 v[106:107], v[106:107], v[140:141] op_sel:[0,1]
	v_pk_mul_f32 v[108:109], v[108:109], v[140:141] op_sel:[0,1]
	v_pk_mul_f32 v[110:111], v[110:111], v[140:141] op_sel:[0,1]
	v_pk_mul_f32 v[112:113], v[112:113], v[142:143] op_sel_hi:[1,0]
	v_pk_mul_f32 v[114:115], v[114:115], v[142:143] op_sel_hi:[1,0]
	v_pk_mul_f32 v[116:117], v[116:117], v[142:143] op_sel_hi:[1,0]
	v_pk_mul_f32 v[118:119], v[118:119], v[142:143] op_sel_hi:[1,0]
	v_pk_mul_f32 v[120:121], v[120:121], v[142:143] op_sel:[0,1]
	v_pk_mul_f32 v[122:123], v[122:123], v[142:143] op_sel:[0,1]
	v_pk_mul_f32 v[124:125], v[124:125], v[142:143] op_sel:[0,1]
	v_pk_mul_f32 v[126:127], v[126:127], v[142:143] op_sel:[0,1]
	v_cvt_pk_bf16_f32 v144, v64, v72
	v_cvt_pk_bf16_f32 v145, v80, v88
	v_cvt_pk_bf16_f32 v146, v96, v104
	v_cvt_pk_bf16_f32 v147, v112, v120
	global_store_dwordx4 v179, v[144:147], s[24:25]
	v_cvt_pk_bf16_f32 v148, v65, v73
	v_cvt_pk_bf16_f32 v149, v81, v89
	v_cvt_pk_bf16_f32 v150, v97, v105
	v_cvt_pk_bf16_f32 v151, v113, v121
	s_add_u32 s24, s24, s26
	s_addc_u32 s25, s25, 0
	global_store_dwordx4 v179, v[148:151], s[24:25]
	v_cvt_pk_bf16_f32 v152, v66, v74
	v_cvt_pk_bf16_f32 v153, v82, v90
	v_cvt_pk_bf16_f32 v154, v98, v106
	v_cvt_pk_bf16_f32 v155, v114, v122
	s_add_u32 s24, s24, s26
	s_addc_u32 s25, s25, 0
	global_store_dwordx4 v179, v[152:155], s[24:25]
	v_cvt_pk_bf16_f32 v156, v67, v75
	v_cvt_pk_bf16_f32 v157, v83, v91
	v_cvt_pk_bf16_f32 v158, v99, v107
	v_cvt_pk_bf16_f32 v159, v115, v123
	s_add_u32 s24, s24, s26
	s_addc_u32 s25, s25, 0
	global_store_dwordx4 v179, v[156:159], s[24:25]
	s_mov_b64 exec, s[48:49]
	v_cvt_pk_bf16_f32 v160, v68, v76
	v_cvt_pk_bf16_f32 v161, v84, v92
	v_cvt_pk_bf16_f32 v162, v100, v108
	v_cvt_pk_bf16_f32 v163, v116, v124
	s_mul_i32 s2, s26, 29
	s_add_u32 s24, s24, s2
	s_addc_u32 s25, s25, 0
	global_store_dwordx4 v184, v[160:163], s[24:25]
	v_cvt_pk_bf16_f32 v164, v69, v77
	v_cvt_pk_bf16_f32 v165, v85, v93
	v_cvt_pk_bf16_f32 v166, v101, v109
	v_cvt_pk_bf16_f32 v167, v117, v125
	s_add_u32 s24, s24, s26
	s_addc_u32 s25, s25, 0
	global_store_dwordx4 v184, v[164:167], s[24:25]
	v_cvt_pk_bf16_f32 v168, v70, v78
	v_cvt_pk_bf16_f32 v169, v86, v94
	v_cvt_pk_bf16_f32 v170, v102, v110
	v_cvt_pk_bf16_f32 v171, v118, v126
	s_add_u32 s24, s24, s26
	s_addc_u32 s25, s25, 0
	global_store_dwordx4 v184, v[168:171], s[24:25]
	v_cvt_pk_bf16_f32 v172, v71, v79
	v_cvt_pk_bf16_f32 v173, v87, v95
	v_cvt_pk_bf16_f32 v174, v103, v111
	v_cvt_pk_bf16_f32 v175, v119, v127
	s_add_u32 s24, s24, s26
	s_addc_u32 s25, s25, 0
	global_store_dwordx4 v184, v[172:175], s[24:25]
	s_mov_b64 exec, -1
	s_cmp_lt_u32 s4, 0x12cf
	s_cbranch_scc1 .Lcv1_lb_go
	s_mov_b32 s28, 0
	s_branch .Lcv1_lb_end

.LBB0_1169:
	s_mul_hi_u32 s0, s53, 0x79b
	s_mul_i32 s0, s0, s52
	s_sub_i32 s0, 0x79b, s0
	s_sub_i32 s1, s0, s52
	s_cmp_ge_u32 s0, s52
	s_cselect_b32 s0, s1, s0
	s_sub_i32 s1, s0, s52
	s_cmp_ge_u32 s0, s52
	s_movk_i32 s7, 0xf4
	s_cmp_lg_u32 s7, 0
	v_readlane_b32 s2, v234, 14
	s_cselect_b64 s[0:1], -1, 0
	s_cmp_ge_i32 s2, s7
	s_cselect_b64 s[2:3], -1, 0
	s_and_b64 s[0:1], s[0:1], s[2:3]
	s_and_b64 vcc, exec, s[0:1]
	s_cbranch_vccz .LBB0_1605
	v_readlane_b32 s2, v234, 14
	v_readlane_b32 s3, v234, 12
	v_readfirstlane_b32 s0, v183
	s_sub_i32 s2, s2, s7
	s_sub_i32 s3, s3, s7
	s_lshl_b32 s2, s2, 3
	s_lshr_b32 s0, s0, 6
	s_add_i32 s4, s2, s0
	s_lshl_b32 s33, s3, 3
	s_cmp_ge_u32 s4, 0x14ec
	s_cbranch_scc1 .LBB0_1605
	v_readlane_b32 s30, v234, 2
	v_readlane_b32 s31, v234, 3
	v_and_b32_e32 v176, 7, v183
	v_bfe_u32 v185, v183, 3, 3
	v_lshlrev_b32_e32 v177, 4, v185
	v_lshlrev_b32_e32 v186, 4, v176
	s_cmp_lt_u32 s4, 0x14ec
	s_cbranch_scc1 .Lcv2_p0_go
	s_mov_b32 s22, 0
	s_branch .Lcv2_p0_end

.Lcv2_p0_seg1:
	s_cmp_lt_u32 s4, 0x9ec
	s_cbranch_scc0 .Lcv2_p0_seg2
	s_add_u32 s34, s4, 0x114
	s_mul_i32 s39, s34, 5958
	s_lshr_b32 s39, s39, 19
	s_mul_i32 s40, s39, 88
	s_sub_u32 s40, s34, s40
	v_readlane_b32 s0, v234, 4
	v_readlane_b32 s1, v234, 5
	s_mul_i32 s2, s39, 0x160000
	s_lshl_b32 s3, s40, 8
	s_add_u32 s2, s2, s3
	s_add_u32 s0, s0, s2
	s_addc_u32 s1, s1, 0
	s_mov_b32 s41, 0x5800
	s_mov_b32 s42, 0x2c000
	s_lshr_b32 s2, s40, 1
	s_lshl_b32 s2, s2, 8
	s_and_b32 s3, s40, 1
	s_lshl_b32 s3, s3, 6
	s_add_u32 s2, s2, s3
	s_mul_i32 s2, s2, 0x1000
	s_lshl_b32 s3, s39, 7
	s_add_u32 s2, s2, s3
	s_add_u32 s2, s2, 0x8700000
	s_add_u32 s16, s30, s2
	s_addc_u32 s17, s31, 0
	s_mov_b32 s20, 0x1000
	s_mov_b32 s21, 0x4000
	s_mov_b32 s23, -1
	v_readlane_b32 s8, v233, 6
	v_readlane_b32 s9, v233, 7
	s_lshl_b32 s3, s39, 8
	s_mov_b32 s22, 18
	s_nop 0
	s_add_u32 s8, s8, s3
	s_addc_u32 s9, s9, 0
	s_branch .Lcv2_p0_ld
.Lcv2_p0_seg2:
	s_sub_u32 s34, s4, 0x9ec
	s_mul_i32 s39, s34, 5958
	s_lshr_b32 s39, s39, 19
	s_mul_i32 s40, s39, 88
	s_sub_u32 s40, s34, s40
	v_readlane_b32 s0, v234, 6
	v_readlane_b32 s1, v234, 7
	s_mul_i32 s2, s39, 0x160000
	s_lshl_b32 s3, s40, 8
	s_add_u32 s2, s2, s3
	s_add_u32 s0, s0, s2
	s_addc_u32 s1, s1, 0
	s_mov_b32 s41, 0x5800
	s_mov_b32 s42, 0x2c000
	s_lshr_b32 s2, s40, 1
	s_lshl_b32 s2, s2, 8
	s_and_b32 s3, s40, 1
	s_lshl_b32 s3, s3, 6
	s_add_u32 s2, s2, s3
	s_add_u32 s2, s2, 0x80
	s_mul_i32 s2, s2, 0x1000
	s_lshl_b32 s3, s39, 7
	s_add_u32 s2, s2, s3
	s_add_u32 s2, s2, 0x8700000
	s_add_u32 s16, s30, s2
	s_addc_u32 s17, s31, 0
	s_mov_b32 s20, 0x1000
	s_mov_b32 s21, 0x4000
	s_mov_b32 s23, -1
	v_readlane_b32 s8, v233, 6
	v_readlane_b32 s9, v233, 7
	s_lshl_b32 s3, s39, 8
	s_mov_b32 s22, 18
	s_nop 0
	s_add_u32 s8, s8, s3
	s_addc_u32 s9, s9, 0

.Lcv2_p0_end:
	s_cmp_lt_u32 s4, 0x14ec
	s_cbranch_scc1 .Lcv2_p1_go
	s_mov_b32 s28, 0
	s_branch .Lcv2_p1_end

.Lcv2_p1_seg1:
	s_cmp_lt_u32 s4, 0x9ec
	s_cbranch_scc0 .Lcv2_p1_seg2
	s_add_u32 s34, s4, 0x114
	s_mul_i32 s39, s34, 5958
	s_lshr_b32 s39, s39, 19
	s_mul_i32 s40, s39, 88
	s_sub_u32 s40, s34, s40
	v_readlane_b32 s0, v234, 4
	v_readlane_b32 s1, v234, 5
	s_mul_i32 s2, s39, 0x160000
	s_lshl_b32 s3, s40, 8
	s_add_u32 s2, s2, s3
	s_add_u32 s0, s0, s2
	s_addc_u32 s1, s1, 0
	s_mov_b32 s41, 0x5800
	s_mov_b32 s42, 0x2c000
	s_lshr_b32 s2, s40, 1
	s_lshl_b32 s2, s2, 8
	s_and_b32 s3, s40, 1
	s_lshl_b32 s3, s3, 6
	s_add_u32 s2, s2, s3
	s_mul_i32 s2, s2, 0x1000
	s_lshl_b32 s3, s39, 7
	s_add_u32 s2, s2, s3
	s_add_u32 s2, s2, 0x8700000
	s_add_u32 s24, s30, s2
	s_addc_u32 s25, s31, 0
	s_mov_b32 s26, 0x1000
	s_mov_b32 s27, 0x4000
	s_mov_b32 s29, -1
	v_readlane_b32 s8, v233, 6
	v_readlane_b32 s9, v233, 7
	s_lshl_b32 s3, s39, 8
	s_mov_b32 s28, 18
	s_nop 0
	s_add_u32 s8, s8, s3
	s_addc_u32 s9, s9, 0
	s_branch .Lcv2_p1_ld
.Lcv2_p1_seg2:
	s_sub_u32 s34, s4, 0x9ec
	s_mul_i32 s39, s34, 5958
	s_lshr_b32 s39, s39, 19
	s_mul_i32 s40, s39, 88
	s_sub_u32 s40, s34, s40
	v_readlane_b32 s0, v234, 6
	v_readlane_b32 s1, v234, 7
	s_mul_i32 s2, s39, 0x160000
	s_lshl_b32 s3, s40, 8
	s_add_u32 s2, s2, s3
	s_add_u32 s0, s0, s2
	s_addc_u32 s1, s1, 0
	s_mov_b32 s41, 0x5800
	s_mov_b32 s42, 0x2c000
	s_lshr_b32 s2, s40, 1
	s_lshl_b32 s2, s2, 8
	s_and_b32 s3, s40, 1
	s_lshl_b32 s3, s3, 6
	s_add_u32 s2, s2, s3
	s_add_u32 s2, s2, 0x80
	s_mul_i32 s2, s2, 0x1000
	s_lshl_b32 s3, s39, 7
	s_add_u32 s2, s2, s3
	s_add_u32 s2, s2, 0x8700000
	s_add_u32 s24, s30, s2
	s_addc_u32 s25, s31, 0
	s_mov_b32 s26, 0x1000
	s_mov_b32 s27, 0x4000
	s_mov_b32 s29, -1
	v_readlane_b32 s8, v233, 6
	v_readlane_b32 s9, v233, 7
	s_lshl_b32 s3, s39, 8
	s_mov_b32 s28, 18
	s_nop 0
	s_add_u32 s8, s8, s3
	s_addc_u32 s9, s9, 0

.Lcv2_pw_wd:
.Lcv2_loop:
	v_mad_u32_u24 v179, v185, s21, v186
	v_pk_mul_f32 v[0:1], v[0:1], v[128:129] op_sel_hi:[1,0]
	v_pk_mul_f32 v[2:3], v[2:3], v[128:129] op_sel_hi:[1,0]
	v_pk_mul_f32 v[4:5], v[4:5], v[128:129] op_sel_hi:[1,0]
	v_pk_mul_f32 v[6:7], v[6:7], v[128:129] op_sel_hi:[1,0]
	v_pk_mul_f32 v[8:9], v[8:9], v[128:129] op_sel:[0,1]
	v_pk_mul_f32 v[10:11], v[10:11], v[128:129] op_sel:[0,1]
	v_pk_mul_f32 v[12:13], v[12:13], v[128:129] op_sel:[0,1]
	v_pk_mul_f32 v[14:15], v[14:15], v[128:129] op_sel:[0,1]
	v_pk_mul_f32 v[16:17], v[16:17], v[130:131] op_sel_hi:[1,0]
	v_pk_mul_f32 v[18:19], v[18:19], v[130:131] op_sel_hi:[1,0]
	v_pk_mul_f32 v[20:21], v[20:21], v[130:131] op_sel_hi:[1,0]
	v_pk_mul_f32 v[22:23], v[22:23], v[130:131] op_sel_hi:[1,0]
	v_pk_mul_f32 v[24:25], v[24:25], v[130:131] op_sel:[0,1]
	v_pk_mul_f32 v[26:27], v[26:27], v[130:131] op_sel:[0,1]
	v_pk_mul_f32 v[28:29], v[28:29], v[130:131] op_sel:[0,1]
	v_pk_mul_f32 v[30:31], v[30:31], v[130:131] op_sel:[0,1]
	v_pk_mul_f32 v[32:33], v[32:33], v[132:133] op_sel_hi:[1,0]
	v_pk_mul_f32 v[34:35], v[34:35], v[132:133] op_sel_hi:[1,0]
	v_pk_mul_f32 v[36:37], v[36:37], v[132:133] op_sel_hi:[1,0]
	v_pk_mul_f32 v[38:39], v[38:39], v[132:133] op_sel_hi:[1,0]
	v_pk_mul_f32 v[40:41], v[40:41], v[132:133] op_sel:[0,1]
	v_pk_mul_f32 v[42:43], v[42:43], v[132:133] op_sel:[0,1]
	v_pk_mul_f32 v[44:45], v[44:45], v[132:133] op_sel:[0,1]
	v_pk_mul_f32 v[46:47], v[46:47], v[132:133] op_sel:[0,1]
	v_pk_mul_f32 v[48:49], v[48:49], v[134:135] op_sel_hi:[1,0]
	v_pk_mul_f32 v[50:51], v[50:51], v[134:135] op_sel_hi:[1,0]
	v_pk_mul_f32 v[52:53], v[52:53], v[134:135] op_sel_hi:[1,0]
	v_pk_mul_f32 v[54:55], v[54:55], v[134:135] op_sel_hi:[1,0]
	v_pk_mul_f32 v[56:57], v[56:57], v[134:135] op_sel:[0,1]
	v_pk_mul_f32 v[58:59], v[58:59], v[134:135] op_sel:[0,1]
	v_pk_mul_f32 v[60:61], v[60:61], v[134:135] op_sel:[0,1]
	v_pk_mul_f32 v[62:63], v[62:63], v[134:135] op_sel:[0,1]
	v_cvt_pk_bf16_f32 v144, v0, v8
	v_cvt_pk_bf16_f32 v145, v16, v24
	v_cvt_pk_bf16_f32 v146, v32, v40
	v_cvt_pk_bf16_f32 v147, v48, v56
	global_store_dwordx4 v179, v[144:147], s[16:17]
	v_cvt_pk_bf16_f32 v148, v1, v9
	v_cvt_pk_bf16_f32 v149, v17, v25
	v_cvt_pk_bf16_f32 v150, v33, v41
	v_cvt_pk_bf16_f32 v151, v49, v57
	s_add_u32 s16, s16, s20
	s_addc_u32 s17, s17, 0
	global_store_dwordx4 v179, v[148:151], s[16:17]
	v_cvt_pk_bf16_f32 v152, v2, v10
	v_cvt_pk_bf16_f32 v153, v18, v26
	v_cvt_pk_bf16_f32 v154, v34, v42
	v_cvt_pk_bf16_f32 v155, v50, v58
	s_add_u32 s16, s16, s20
	s_addc_u32 s17, s17, 0
	global_store_dwordx4 v179, v[152:155], s[16:17]
	v_cvt_pk_bf16_f32 v156, v3, v11
	v_cvt_pk_bf16_f32 v157, v19, v27
	v_cvt_pk_bf16_f32 v158, v35, v43
	v_cvt_pk_bf16_f32 v159, v51, v59
	s_add_u32 s16, s16, s20
	s_addc_u32 s17, s17, 0
	global_store_dwordx4 v179, v[156:159], s[16:17]
	v_cvt_pk_bf16_f32 v160, v4, v12
	v_cvt_pk_bf16_f32 v161, v20, v28
	v_cvt_pk_bf16_f32 v162, v36, v44
	v_cvt_pk_bf16_f32 v163, v52, v60
	s_mul_i32 s2, s20, 29
	s_add_u32 s16, s16, s2
	s_addc_u32 s17, s17, 0
	global_store_dwordx4 v179, v[160:163], s[16:17]
	v_cvt_pk_bf16_f32 v164, v5, v13
	v_cvt_pk_bf16_f32 v165, v21, v29
	v_cvt_pk_bf16_f32 v166, v37, v45
	v_cvt_pk_bf16_f32 v167, v53, v61
	s_add_u32 s16, s16, s20
	s_addc_u32 s17, s17, 0
	global_store_dwordx4 v179, v[164:167], s[16:17]
	v_cvt_pk_bf16_f32 v168, v6, v14
	v_cvt_pk_bf16_f32 v169, v22, v30
	v_cvt_pk_bf16_f32 v170, v38, v46
	v_cvt_pk_bf16_f32 v171, v54, v62
	s_add_u32 s16, s16, s20
	s_addc_u32 s17, s17, 0
	global_store_dwordx4 v179, v[168:171], s[16:17]
	v_cvt_pk_bf16_f32 v172, v7, v15
	v_cvt_pk_bf16_f32 v173, v23, v31
	v_cvt_pk_bf16_f32 v174, v39, v47
	v_cvt_pk_bf16_f32 v175, v55, v63
	s_add_u32 s16, s16, s20
	s_addc_u32 s17, s17, 0
	global_store_dwordx4 v179, v[172:175], s[16:17]
	s_cmp_lt_u32 s4, 0x14ec
	s_cbranch_scc1 .Lcv2_la_go
	s_mov_b32 s22, 0
	s_branch .Lcv2_la_end

.Lcv2_wb_wd:
	v_mad_u32_u24 v179, v185, s27, v186
	v_pk_mul_f32 v[64:65], v[64:65], v[136:137] op_sel_hi:[1,0]
	v_pk_mul_f32 v[66:67], v[66:67], v[136:137] op_sel_hi:[1,0]
	v_pk_mul_f32 v[68:69], v[68:69], v[136:137] op_sel_hi:[1,0]
	v_pk_mul_f32 v[70:71], v[70:71], v[136:137] op_sel_hi:[1,0]
	v_pk_mul_f32 v[72:73], v[72:73], v[136:137] op_sel:[0,1]
	v_pk_mul_f32 v[74:75], v[74:75], v[136:137] op_sel:[0,1]
	v_pk_mul_f32 v[76:77], v[76:77], v[136:137] op_sel:[0,1]
	v_pk_mul_f32 v[78:79], v[78:79], v[136:137] op_sel:[0,1]
	v_pk_mul_f32 v[80:81], v[80:81], v[138:139] op_sel_hi:[1,0]
	v_pk_mul_f32 v[82:83], v[82:83], v[138:139] op_sel_hi:[1,0]
	v_pk_mul_f32 v[84:85], v[84:85], v[138:139] op_sel_hi:[1,0]
	v_pk_mul_f32 v[86:87], v[86:87], v[138:139] op_sel_hi:[1,0]
	v_pk_mul_f32 v[88:89], v[88:89], v[138:139] op_sel:[0,1]
	v_pk_mul_f32 v[90:91], v[90:91], v[138:139] op_sel:[0,1]
	v_pk_mul_f32 v[92:93], v[92:93], v[138:139] op_sel:[0,1]
	v_pk_mul_f32 v[94:95], v[94:95], v[138:139] op_sel:[0,1]
	v_pk_mul_f32 v[96:97], v[96:97], v[140:141] op_sel_hi:[1,0]
	v_pk_mul_f32 v[98:99], v[98:99], v[140:141] op_sel_hi:[1,0]
	v_pk_mul_f32 v[100:101], v[100:101], v[140:141] op_sel_hi:[1,0]
	v_pk_mul_f32 v[102:103], v[102:103], v[140:141] op_sel_hi:[1,0]
	v_pk_mul_f32 v[104:105], v[104:105], v[140:141] op_sel:[0,1]
	v_pk_mul_f32 v[106:107], v[106:107], v[140:141] op_sel:[0,1]
	v_pk_mul_f32 v[108:109], v[108:109], v[140:141] op_sel:[0,1]
	v_pk_mul_f32 v[110:111], v[110:111], v[140:141] op_sel:[0,1]
	v_pk_mul_f32 v[112:113], v[112:113], v[142:143] op_sel_hi:[1,0]
	v_pk_mul_f32 v[114:115], v[114:115], v[142:143] op_sel_hi:[1,0]
	v_pk_mul_f32 v[116:117], v[116:117], v[142:143] op_sel_hi:[1,0]
	v_pk_mul_f32 v[118:119], v[118:119], v[142:143] op_sel_hi:[1,0]
	v_pk_mul_f32 v[120:121], v[120:121], v[142:143] op_sel:[0,1]
	v_pk_mul_f32 v[122:123], v[122:123], v[142:143] op_sel:[0,1]
	v_pk_mul_f32 v[124:125], v[124:125], v[142:143] op_sel:[0,1]
	v_pk_mul_f32 v[126:127], v[126:127], v[142:143] op_sel:[0,1]
	v_cvt_pk_bf16_f32 v144, v64, v72
	v_cvt_pk_bf16_f32 v145, v80, v88
	v_cvt_pk_bf16_f32 v146, v96, v104
	v_cvt_pk_bf16_f32 v147, v112, v120
	global_store_dwordx4 v179, v[144:147], s[24:25]
	v_cvt_pk_bf16_f32 v148, v65, v73
	v_cvt_pk_bf16_f32 v149, v81, v89
	v_cvt_pk_bf16_f32 v150, v97, v105
	v_cvt_pk_bf16_f32 v151, v113, v121
	s_add_u32 s24, s24, s26
	s_addc_u32 s25, s25, 0
	global_store_dwordx4 v179, v[148:151], s[24:25]
	v_cvt_pk_bf16_f32 v152, v66, v74
	v_cvt_pk_bf16_f32 v153, v82, v90
	v_cvt_pk_bf16_f32 v154, v98, v106
	v_cvt_pk_bf16_f32 v155, v114, v122
	s_add_u32 s24, s24, s26
	s_addc_u32 s25, s25, 0
	global_store_dwordx4 v179, v[152:155], s[24:25]
	v_cvt_pk_bf16_f32 v156, v67, v75
	v_cvt_pk_bf16_f32 v157, v83, v91
	v_cvt_pk_bf16_f32 v158, v99, v107
	v_cvt_pk_bf16_f32 v159, v115, v123
	s_add_u32 s24, s24, s26
	s_addc_u32 s25, s25, 0
	global_store_dwordx4 v179, v[156:159], s[24:25]
	v_cvt_pk_bf16_f32 v160, v68, v76
	v_cvt_pk_bf16_f32 v161, v84, v92
	v_cvt_pk_bf16_f32 v162, v100, v108
	v_cvt_pk_bf16_f32 v163, v116, v124
	s_mul_i32 s2, s26, 29
	s_add_u32 s24, s24, s2
	s_addc_u32 s25, s25, 0
	global_store_dwordx4 v179, v[160:163], s[24:25]
	v_cvt_pk_bf16_f32 v164, v69, v77
	v_cvt_pk_bf16_f32 v165, v85, v93
	v_cvt_pk_bf16_f32 v166, v101, v109
	v_cvt_pk_bf16_f32 v167, v117, v125
	s_add_u32 s24, s24, s26
	s_addc_u32 s25, s25, 0
	global_store_dwordx4 v179, v[164:167], s[24:25]
	v_cvt_pk_bf16_f32 v168, v70, v78
	v_cvt_pk_bf16_f32 v169, v86, v94
	v_cvt_pk_bf16_f32 v170, v102, v110
	v_cvt_pk_bf16_f32 v171, v118, v126
	s_add_u32 s24, s24, s26
	s_addc_u32 s25, s25, 0
	global_store_dwordx4 v179, v[168:171], s[24:25]
	v_cvt_pk_bf16_f32 v172, v71, v79
	v_cvt_pk_bf16_f32 v173, v87, v95
	v_cvt_pk_bf16_f32 v174, v103, v111
	v_cvt_pk_bf16_f32 v175, v119, v127
	s_add_u32 s24, s24, s26
	s_addc_u32 s25, s25, 0
	global_store_dwordx4 v179, v[172:175], s[24:25]
	s_cmp_lt_u32 s4, 0x14ec
	s_cbranch_scc1 .Lcv2_lb_go
	s_mov_b32 s28, 0
	s_branch .Lcv2_lb_end
